# 7.11 extended: next iteration's slot addresses (v250-253), prefetch pointers and k0/bias offsets also computed in front of the loop-back barrier; loop head = 4 tile stores + 4 prefetch loads + active
# baseline (speedup 1.0000x reference)
.LBB0_649:
	s_add_i32 s27, s0, -2
	s_and_b32 s27, s27, 1
	s_xor_b32 s34, s27, 1
	s_mul_i32 s35, s34, 0x4400
	v_add3_u32 v250, s35, v157, v158
	v_add3_u32 v251, s68, v159, v158
	v_add3_u32 v252, s35, v160, v161
	v_add3_u32 v253, s68, v147, v161
	s_cmp_lt_u32 s0, s1
	s_cselect_b32 s34, s0, s6
	s_sub_i32 s34, s6, s34
	s_lshl_b32 s34, s34, 20
	s_add_u32 s80, s78, s34
	s_addc_u32 s81, s79, 0
	s_add_u32 s80, s80, 0x1000
	s_addc_u32 s81, s81, 0
	s_add_u32 s82, s80, 0x1000
	s_addc_u32 s83, s81, 0
	s_lshr_b32 s77, s7, 2
	s_sub_i32 s77, s77, s26
	s_add_i32 s77, s77, -1
	s_sub_i32 s75, s7, s4
	s_add_i32 s75, s75, -256
.Lff1a_top2:
	s_waitcnt vmcnt(3)
	ds_write_b128 v250, v[130:133]
	s_waitcnt vmcnt(2)
	ds_write_b128 v251, v[134:137] offset:34816
	s_waitcnt vmcnt(1)
	ds_write_b128 v252, v[138:141]
	s_waitcnt vmcnt(0)
	ds_write_b128 v253, v[142:145] offset:34816
	global_load_dwordx4 v[130:133], v150, s[80:81]
	global_load_dwordx4 v[134:137], v150, s[82:83]
	global_load_dwordx4 v[138:141], v152, s[80:81]
	global_load_dwordx4 v[142:145], v152, s[82:83]
	s_cmp_gt_i32 s77, s5
	s_cbranch_scc1 .Lff1a_inact
	s_cmp_eq_u32 s72, 0
	s_cbranch_scc1 .Lff1a_first
	s_mul_i32 s34, s27, 0x4400
	v_add_u32_e32 v0, s34, v162
	ds_read_b128 v[198:201], v0
	ds_read_b128 v[202:205], v0 offset:32
	ds_read_b128 v[206:209], v0 offset:8704
	ds_read_b128 v[210:213], v0 offset:8736
	v_add_u32_e32 v246, s75, v149
	v_add_u32_e32 v234, 0x12800, v246
	v_add_u32_e32 v235, 0x12880, v246
	v_add_u32_e32 v238, 0x12820, v246
	v_add_u32_e32 v239, 0x128a0, v246
	v_add_u32_e32 v242, 0x12840, v246
	v_add_u32_e32 v243, 0x128c0, v246
	v_add_u32_e32 v247, 0x12860, v246
	v_add_u32_e32 v246, 0x128e0, v246
	ds_read_b128 v[218:221], v234
	ds_read_b128 v[234:237], v235
	ds_read_b128 v[222:225], v238
	ds_read_b128 v[238:241], v239
	ds_read_b128 v[226:229], v242
	ds_read_b128 v[242:245], v243
	ds_read_b128 v[230:233], v247
	ds_read_b128 v[246:249], v246
	s_waitcnt lgkmcnt(1)
	v_mfma_f32_32x32x16_bf16 v[218:233], v[198:201], v[98:101], v[218:233]
	v_sub_f32_e32 v82, v82, v197
	v_sub_f32_e32 v83, v83, v197
	v_sub_f32_e32 v84, v84, v197
	v_sub_f32_e32 v85, v85, v197
	v_exp_f32_e32 v82, v82
	v_exp_f32_e32 v83, v83
	v_exp_f32_e32 v84, v84
	v_exp_f32_e32 v85, v85
	s_waitcnt lgkmcnt(0)
	v_mfma_f32_32x32x16_bf16 v[234:249], v[206:209], v[98:101], v[234:249]
	v_sub_f32_e32 v86, v86, v197
	v_sub_f32_e32 v87, v87, v197
	v_sub_f32_e32 v88, v88, v197
	v_sub_f32_e32 v89, v89, v197
	v_exp_f32_e32 v86, v86
	v_exp_f32_e32 v87, v87
	v_exp_f32_e32 v88, v88
	v_exp_f32_e32 v89, v89
	v_mfma_f32_32x32x16_bf16 v[218:233], v[202:205], v[102:105], v[218:233]
	v_sub_f32_e32 v66, v66, v197
	v_sub_f32_e32 v67, v67, v197
	v_sub_f32_e32 v68, v68, v197
	v_sub_f32_e32 v69, v69, v197
	v_exp_f32_e32 v66, v66
	v_exp_f32_e32 v67, v67
	v_exp_f32_e32 v68, v68
	v_exp_f32_e32 v69, v69
	ds_read_b128 v[198:201], v0 offset:64
	ds_read_b128 v[202:205], v0 offset:96
	ds_read_b128 v[206:209], v0 offset:8768
	ds_read_b128 v[214:217], v0 offset:8800
	v_mfma_f32_32x32x16_bf16 v[234:249], v[210:213], v[102:105], v[234:249]
	v_add_f32_e32 v250, v82, v86
	v_add_f32_e32 v251, v83, v87
	v_add_f32_e32 v252, v84, v88
	v_add_f32_e32 v253, v85, v89
	v_sub_f32_e32 v70, v70, v197
	v_sub_f32_e32 v71, v71, v197
	v_sub_f32_e32 v72, v72, v197
	v_sub_f32_e32 v73, v73, v197
	s_waitcnt lgkmcnt(3)
	v_mfma_f32_32x32x16_bf16 v[218:233], v[198:201], v[106:109], v[218:233]
	v_exp_f32_e32 v70, v70
	v_exp_f32_e32 v71, v71
	v_exp_f32_e32 v72, v72
	v_exp_f32_e32 v73, v73
	v_add_f32_e32 v250, v250, v66
	v_add_f32_e32 v251, v251, v67
	v_add_f32_e32 v252, v252, v68
	v_add_f32_e32 v253, v253, v69
	s_waitcnt lgkmcnt(1)
	v_mfma_f32_32x32x16_bf16 v[234:249], v[206:209], v[106:109], v[234:249]
	v_sub_f32_e32 v90, v90, v197
	v_sub_f32_e32 v91, v91, v197
	v_sub_f32_e32 v92, v92, v197
	v_sub_f32_e32 v93, v93, v197
	v_exp_f32_e32 v90, v90
	v_exp_f32_e32 v91, v91
	v_exp_f32_e32 v92, v92
	v_exp_f32_e32 v93, v93
	v_mfma_f32_32x32x16_bf16 v[218:233], v[202:205], v[110:113], v[218:233]
	v_add_f32_e32 v250, v250, v70
	v_add_f32_e32 v251, v251, v71
	v_add_f32_e32 v252, v252, v72
	v_add_f32_e32 v253, v253, v73
	v_sub_f32_e32 v94, v94, v197
	v_sub_f32_e32 v95, v95, v197
	v_sub_f32_e32 v96, v96, v197
	v_sub_f32_e32 v97, v97, v197
	ds_read_b128 v[198:201], v0 offset:128
	ds_read_b128 v[202:205], v0 offset:160
	ds_read_b128 v[206:209], v0 offset:8832
	ds_read_b128 v[210:213], v0 offset:8864
	s_waitcnt lgkmcnt(4)
	v_mfma_f32_32x32x16_bf16 v[234:249], v[214:217], v[110:113], v[234:249]
	v_exp_f32_e32 v94, v94
	v_exp_f32_e32 v95, v95
	v_exp_f32_e32 v96, v96
	v_exp_f32_e32 v97, v97
	v_add_f32_e32 v250, v250, v90
	v_add_f32_e32 v251, v251, v91
	v_add_f32_e32 v252, v252, v92
	v_add_f32_e32 v253, v253, v93
	s_waitcnt lgkmcnt(3)
	v_mfma_f32_32x32x16_bf16 v[218:233], v[198:201], v[114:117], v[218:233]
	v_sub_f32_e32 v74, v74, v197
	v_sub_f32_e32 v75, v75, v197
	v_sub_f32_e32 v76, v76, v197
	v_sub_f32_e32 v77, v77, v197
	v_exp_f32_e32 v74, v74
	v_exp_f32_e32 v75, v75
	v_exp_f32_e32 v76, v76
	v_exp_f32_e32 v77, v77
	s_waitcnt lgkmcnt(1)
	v_mfma_f32_32x32x16_bf16 v[234:249], v[206:209], v[114:117], v[234:249]
	v_add_f32_e32 v250, v250, v94
	v_add_f32_e32 v251, v251, v95
	v_add_f32_e32 v252, v252, v96
	v_add_f32_e32 v253, v253, v97
	v_sub_f32_e32 v78, v78, v197
	v_sub_f32_e32 v79, v79, v197
	v_sub_f32_e32 v80, v80, v197
	v_sub_f32_e32 v81, v81, v197
	v_mfma_f32_32x32x16_bf16 v[218:233], v[202:205], v[118:121], v[218:233]
	v_exp_f32_e32 v78, v78
	v_exp_f32_e32 v79, v79
	v_exp_f32_e32 v80, v80
	v_exp_f32_e32 v81, v81
	v_add_f32_e32 v250, v250, v74
	v_add_f32_e32 v251, v251, v75
	v_add_f32_e32 v252, v252, v76
	v_add_f32_e32 v253, v253, v77
	ds_read_b128 v[198:201], v0 offset:192
	ds_read_b128 v[202:205], v0 offset:224
	ds_read_b128 v[206:209], v0 offset:8896
	ds_read_b128 v[214:217], v0 offset:8928
	s_waitcnt lgkmcnt(4)
	v_mfma_f32_32x32x16_bf16 v[234:249], v[210:213], v[118:121], v[234:249]
	v_add_f32_e32 v250, v250, v78
	v_add_f32_e32 v251, v251, v79
	v_add_f32_e32 v252, v252, v80
	v_add_f32_e32 v253, v253, v81
	v_add_f32_e32 v250, v250, v251
	v_add_f32_e32 v252, v252, v253
	v_add_f32_e32 v250, v250, v252
	v_add_f32_e32 v196, v196, v250
	s_waitcnt lgkmcnt(3)
	v_mfma_f32_32x32x16_bf16 v[218:233], v[198:201], v[122:125], v[218:233]
	v_cvt_pk_bf16_f32 v73, v72, v73
	v_cvt_pk_bf16_f32 v72, v70, v71
	v_cvt_pk_bf16_f32 v71, v68, v69
	v_cvt_pk_bf16_f32 v70, v66, v67
	v_cvt_pk_bf16_f32 v66, v82, v83
	v_cvt_pk_bf16_f32 v67, v84, v85
	v_cvt_pk_bf16_f32 v68, v86, v87
	v_cvt_pk_bf16_f32 v69, v88, v89
	s_waitcnt lgkmcnt(1)
	v_mfma_f32_32x32x16_bf16 v[234:249], v[206:209], v[122:125], v[234:249]
	v_cvt_pk_bf16_f32 v81, v80, v81
	v_cvt_pk_bf16_f32 v80, v78, v79
	v_cvt_pk_bf16_f32 v79, v76, v77
	v_cvt_pk_bf16_f32 v78, v74, v75
	v_cvt_pk_bf16_f32 v74, v90, v91
	v_cvt_pk_bf16_f32 v75, v92, v93
	v_cvt_pk_bf16_f32 v76, v94, v95
	v_cvt_pk_bf16_f32 v77, v96, v97
	v_mfma_f32_32x32x16_bf16 v[218:233], v[202:205], v[126:129], v[218:233]
	s_waitcnt lgkmcnt(0)
	v_mfma_f32_32x32x16_bf16 v[234:249], v[214:217], v[126:129], v[234:249]
	s_add_i32 s76, s77, 63
	s_cmp_le_i32 s76, s5
	s_cbranch_scc1 .Lff1a_z2
	v_cmp_le_i32_e32 vcc, v165, v195
	s_nop 8
	v_cndmask_b32_e32 v234, v155, v234, vcc
	v_cmp_lt_i32_e32 vcc, v163, v195
	s_nop 1
	v_cndmask_b32_e32 v219, v155, v219, vcc
	v_cmp_le_i32_e32 vcc, v163, v195
	s_nop 1
	v_cndmask_b32_e32 v218, v155, v218, vcc
	v_cmp_le_i32_e32 vcc, v166, v195
	s_nop 1
	v_cndmask_b32_e32 v235, v155, v235, vcc
	v_cmp_le_i32_e32 vcc, v167, v195
	s_nop 1
	v_cndmask_b32_e32 v220, v155, v220, vcc
	v_cmp_le_i32_e32 vcc, v168, v195
	s_nop 1
	v_cndmask_b32_e32 v236, v155, v236, vcc
	v_cmp_le_i32_e32 vcc, v169, v195
	s_nop 1
	v_cndmask_b32_e32 v221, v155, v221, vcc
	v_cmp_le_i32_e32 vcc, v170, v195
	s_nop 1
	v_cndmask_b32_e32 v237, v155, v237, vcc
	v_cmp_le_i32_e32 vcc, v171, v195
	s_nop 1
	v_cndmask_b32_e32 v222, v155, v222, vcc
	v_cmp_le_i32_e32 vcc, v172, v195
	s_nop 1
	v_cndmask_b32_e32 v238, v155, v238, vcc
	v_cmp_le_i32_e32 vcc, v173, v195
	s_nop 1
	v_cndmask_b32_e32 v223, v155, v223, vcc
	v_cmp_le_i32_e32 vcc, v174, v195
	s_nop 1
	v_cndmask_b32_e32 v239, v155, v239, vcc
	v_cmp_le_i32_e32 vcc, v175, v195
	s_nop 1
	v_cndmask_b32_e32 v224, v155, v224, vcc
	v_cmp_le_i32_e32 vcc, v176, v195
	s_nop 1
	v_cndmask_b32_e32 v240, v155, v240, vcc
	v_cmp_le_i32_e32 vcc, v177, v195
	s_nop 1
	v_cndmask_b32_e32 v225, v155, v225, vcc
	v_cmp_le_i32_e32 vcc, v178, v195
	s_nop 1
	v_cndmask_b32_e32 v241, v155, v241, vcc
	v_cmp_le_i32_e32 vcc, v179, v195
	s_nop 1
	v_cndmask_b32_e32 v226, v155, v226, vcc
	v_cmp_le_i32_e32 vcc, v180, v195
	s_nop 1
	v_cndmask_b32_e32 v242, v155, v242, vcc
	v_cmp_le_i32_e32 vcc, v181, v195
	s_nop 1
	v_cndmask_b32_e32 v227, v155, v227, vcc
	v_cmp_le_i32_e32 vcc, v182, v195
	s_nop 1
	v_cndmask_b32_e32 v243, v155, v243, vcc
	v_cmp_le_i32_e32 vcc, v183, v195
	s_nop 1
	v_cndmask_b32_e32 v228, v155, v228, vcc
	v_cmp_le_i32_e32 vcc, v184, v195
	s_nop 1
	v_cndmask_b32_e32 v244, v155, v244, vcc
	v_cmp_le_i32_e32 vcc, v185, v195
	s_nop 1
	v_cndmask_b32_e32 v229, v155, v229, vcc
	v_cmp_le_i32_e32 vcc, v186, v195
	s_nop 1
	v_cndmask_b32_e32 v245, v155, v245, vcc
	v_cmp_le_i32_e32 vcc, v187, v195
	s_nop 1
	v_cndmask_b32_e32 v230, v155, v230, vcc
	v_cmp_le_i32_e32 vcc, v188, v195
	s_nop 1
	v_cndmask_b32_e32 v246, v155, v246, vcc
	v_cmp_le_i32_e32 vcc, v189, v195
	s_nop 1
	v_cndmask_b32_e32 v231, v155, v231, vcc
	v_cmp_le_i32_e32 vcc, v190, v195
	s_nop 1
	v_cndmask_b32_e32 v247, v155, v247, vcc
	v_cmp_le_i32_e32 vcc, v191, v195
	s_nop 1
	v_cndmask_b32_e32 v232, v155, v232, vcc
	v_cmp_le_i32_e32 vcc, v192, v195
	s_nop 1
	v_cndmask_b32_e32 v248, v155, v248, vcc
	v_cmp_le_i32_e32 vcc, v193, v195
	s_nop 1
	v_cndmask_b32_e32 v233, v155, v233, vcc
	v_cmp_le_i32_e32 vcc, v194, v195
	s_nop 1
	v_cndmask_b32_e32 v249, v155, v249, vcc

.Lff1a_bar:
	s_mov_b32 s71, s70
	s_mov_b32 s70, s69
	s_mov_b32 s69, s68
	s_mov_b32 s68, s71
	s_addk_i32 s4, 0x100
	s_add_i32 s26, s26, 64
	s_add_i32 s0, s0, 1
	v_add_u32_e32 v195, 64, v195
	s_add_i32 s27, s0, -2
	s_and_b32 s27, s27, 1
	s_xor_b32 s34, s27, 1
	s_mul_i32 s35, s34, 0x4400
	v_add3_u32 v250, s35, v157, v158
	v_add3_u32 v251, s68, v159, v158
	v_add3_u32 v252, s35, v160, v161
	v_add3_u32 v253, s68, v147, v161
	s_cmp_lt_u32 s0, s1
	s_cselect_b32 s34, s0, s6
	s_sub_i32 s34, s6, s34
	s_lshl_b32 s34, s34, 20
	s_add_u32 s80, s78, s34
	s_addc_u32 s81, s79, 0
	s_add_u32 s80, s80, 0x1000
	s_addc_u32 s81, s81, 0
	s_add_u32 s82, s80, 0x1000
	s_addc_u32 s83, s81, 0
	s_lshr_b32 s77, s7, 2
	s_sub_i32 s77, s77, s26
	s_add_i32 s77, s77, -1
	s_sub_i32 s75, s7, s4
	s_add_i32 s75, s75, -256
	s_cmp_lg_u32 s7, s4
	s_waitcnt lgkmcnt(0)
	s_barrier
	s_cbranch_scc0 .Lff1a_exit
	s_branch .Lff1b_top2

.Lff1b_top2:
	s_waitcnt vmcnt(3)
	ds_write_b128 v250, v[130:133]
	s_waitcnt vmcnt(2)
	ds_write_b128 v251, v[134:137] offset:34816
	s_waitcnt vmcnt(1)
	ds_write_b128 v252, v[138:141]
	s_waitcnt vmcnt(0)
	ds_write_b128 v253, v[142:145] offset:34816
	global_load_dwordx4 v[130:133], v150, s[80:81]
	global_load_dwordx4 v[134:137], v150, s[82:83]
	global_load_dwordx4 v[138:141], v152, s[80:81]
	global_load_dwordx4 v[142:145], v152, s[82:83]
	s_cmp_gt_i32 s77, s5
	s_cbranch_scc1 .Lff1b_inact
	s_cmp_eq_u32 s72, 0
	s_cbranch_scc1 .Lff1b_first
	s_mul_i32 s34, s27, 0x4400
	v_add_u32_e32 v0, s34, v162
	ds_read_b128 v[198:201], v0
	ds_read_b128 v[202:205], v0 offset:32
	ds_read_b128 v[206:209], v0 offset:8704
	ds_read_b128 v[210:213], v0 offset:8736
	v_add_u32_e32 v78, s75, v149
	v_add_u32_e32 v66, 0x12800, v78
	v_add_u32_e32 v67, 0x12880, v78
	v_add_u32_e32 v70, 0x12820, v78
	v_add_u32_e32 v71, 0x128a0, v78
	v_add_u32_e32 v74, 0x12840, v78
	v_add_u32_e32 v75, 0x128c0, v78
	v_add_u32_e32 v79, 0x12860, v78
	v_add_u32_e32 v78, 0x128e0, v78
	ds_read_b128 v[82:85], v66
	ds_read_b128 v[66:69], v67
	ds_read_b128 v[86:89], v70
	ds_read_b128 v[70:73], v71
	ds_read_b128 v[90:93], v74
	ds_read_b128 v[74:77], v75
	ds_read_b128 v[94:97], v79
	ds_read_b128 v[78:81], v78
	s_waitcnt lgkmcnt(1)
	v_mfma_f32_32x32x16_bf16 v[82:97], v[198:201], v[98:101], v[82:97]
	v_sub_f32_e32 v218, v218, v197
	v_sub_f32_e32 v219, v219, v197
	v_sub_f32_e32 v220, v220, v197
	v_sub_f32_e32 v221, v221, v197
	v_exp_f32_e32 v218, v218
	v_exp_f32_e32 v219, v219
	v_exp_f32_e32 v220, v220
	v_exp_f32_e32 v221, v221
	s_waitcnt lgkmcnt(0)
	v_mfma_f32_32x32x16_bf16 v[66:81], v[206:209], v[98:101], v[66:81]
	v_sub_f32_e32 v222, v222, v197
	v_sub_f32_e32 v223, v223, v197
	v_sub_f32_e32 v224, v224, v197
	v_sub_f32_e32 v225, v225, v197
	v_exp_f32_e32 v222, v222
	v_exp_f32_e32 v223, v223
	v_exp_f32_e32 v224, v224
	v_exp_f32_e32 v225, v225
	v_mfma_f32_32x32x16_bf16 v[82:97], v[202:205], v[102:105], v[82:97]
	v_sub_f32_e32 v234, v234, v197
	v_sub_f32_e32 v235, v235, v197
	v_sub_f32_e32 v236, v236, v197
	v_sub_f32_e32 v237, v237, v197
	v_exp_f32_e32 v234, v234
	v_exp_f32_e32 v235, v235
	v_exp_f32_e32 v236, v236
	v_exp_f32_e32 v237, v237
	ds_read_b128 v[198:201], v0 offset:64
	ds_read_b128 v[202:205], v0 offset:96
	ds_read_b128 v[206:209], v0 offset:8768
	ds_read_b128 v[214:217], v0 offset:8800
	v_mfma_f32_32x32x16_bf16 v[66:81], v[210:213], v[102:105], v[66:81]
	v_add_f32_e32 v250, v218, v222
	v_add_f32_e32 v251, v219, v223
	v_add_f32_e32 v252, v220, v224
	v_add_f32_e32 v253, v221, v225
	v_sub_f32_e32 v238, v238, v197
	v_sub_f32_e32 v239, v239, v197
	v_sub_f32_e32 v240, v240, v197
	v_sub_f32_e32 v241, v241, v197
	s_waitcnt lgkmcnt(3)
	v_mfma_f32_32x32x16_bf16 v[82:97], v[198:201], v[106:109], v[82:97]
	v_exp_f32_e32 v238, v238
	v_exp_f32_e32 v239, v239
	v_exp_f32_e32 v240, v240
	v_exp_f32_e32 v241, v241
	v_add_f32_e32 v250, v250, v234
	v_add_f32_e32 v251, v251, v235
	v_add_f32_e32 v252, v252, v236
	v_add_f32_e32 v253, v253, v237
	s_waitcnt lgkmcnt(1)
	v_mfma_f32_32x32x16_bf16 v[66:81], v[206:209], v[106:109], v[66:81]
	v_sub_f32_e32 v226, v226, v197
	v_sub_f32_e32 v227, v227, v197
	v_sub_f32_e32 v228, v228, v197
	v_sub_f32_e32 v229, v229, v197
	v_exp_f32_e32 v226, v226
	v_exp_f32_e32 v227, v227
	v_exp_f32_e32 v228, v228
	v_exp_f32_e32 v229, v229
	v_mfma_f32_32x32x16_bf16 v[82:97], v[202:205], v[110:113], v[82:97]
	v_add_f32_e32 v250, v250, v238
	v_add_f32_e32 v251, v251, v239
	v_add_f32_e32 v252, v252, v240
	v_add_f32_e32 v253, v253, v241
	v_sub_f32_e32 v230, v230, v197
	v_sub_f32_e32 v231, v231, v197
	v_sub_f32_e32 v232, v232, v197
	v_sub_f32_e32 v233, v233, v197
	ds_read_b128 v[198:201], v0 offset:128
	ds_read_b128 v[202:205], v0 offset:160
	ds_read_b128 v[206:209], v0 offset:8832
	ds_read_b128 v[210:213], v0 offset:8864
	s_waitcnt lgkmcnt(4)
	v_mfma_f32_32x32x16_bf16 v[66:81], v[214:217], v[110:113], v[66:81]
	v_exp_f32_e32 v230, v230
	v_exp_f32_e32 v231, v231
	v_exp_f32_e32 v232, v232
	v_exp_f32_e32 v233, v233
	v_add_f32_e32 v250, v250, v226
	v_add_f32_e32 v251, v251, v227
	v_add_f32_e32 v252, v252, v228
	v_add_f32_e32 v253, v253, v229
	s_waitcnt lgkmcnt(3)
	v_mfma_f32_32x32x16_bf16 v[82:97], v[198:201], v[114:117], v[82:97]
	v_sub_f32_e32 v242, v242, v197
	v_sub_f32_e32 v243, v243, v197
	v_sub_f32_e32 v244, v244, v197
	v_sub_f32_e32 v245, v245, v197
	v_exp_f32_e32 v242, v242
	v_exp_f32_e32 v243, v243
	v_exp_f32_e32 v244, v244
	v_exp_f32_e32 v245, v245
	s_waitcnt lgkmcnt(1)
	v_mfma_f32_32x32x16_bf16 v[66:81], v[206:209], v[114:117], v[66:81]
	v_add_f32_e32 v250, v250, v230
	v_add_f32_e32 v251, v251, v231
	v_add_f32_e32 v252, v252, v232
	v_add_f32_e32 v253, v253, v233
	v_sub_f32_e32 v246, v246, v197
	v_sub_f32_e32 v247, v247, v197
	v_sub_f32_e32 v248, v248, v197
	v_sub_f32_e32 v249, v249, v197
	v_mfma_f32_32x32x16_bf16 v[82:97], v[202:205], v[118:121], v[82:97]
	v_exp_f32_e32 v246, v246
	v_exp_f32_e32 v247, v247
	v_exp_f32_e32 v248, v248
	v_exp_f32_e32 v249, v249
	v_add_f32_e32 v250, v250, v242
	v_add_f32_e32 v251, v251, v243
	v_add_f32_e32 v252, v252, v244
	v_add_f32_e32 v253, v253, v245
	ds_read_b128 v[198:201], v0 offset:192
	ds_read_b128 v[202:205], v0 offset:224
	ds_read_b128 v[206:209], v0 offset:8896
	ds_read_b128 v[214:217], v0 offset:8928
	s_waitcnt lgkmcnt(4)
	v_mfma_f32_32x32x16_bf16 v[66:81], v[210:213], v[118:121], v[66:81]
	v_add_f32_e32 v250, v250, v246
	v_add_f32_e32 v251, v251, v247
	v_add_f32_e32 v252, v252, v248
	v_add_f32_e32 v253, v253, v249
	v_add_f32_e32 v250, v250, v251
	v_add_f32_e32 v252, v252, v253
	v_add_f32_e32 v250, v250, v252
	v_add_f32_e32 v196, v196, v250
	s_waitcnt lgkmcnt(3)
	v_mfma_f32_32x32x16_bf16 v[82:97], v[198:201], v[122:125], v[82:97]
	v_cvt_pk_bf16_f32 v241, v240, v241
	v_cvt_pk_bf16_f32 v240, v238, v239
	v_cvt_pk_bf16_f32 v239, v236, v237
	v_cvt_pk_bf16_f32 v238, v234, v235
	v_cvt_pk_bf16_f32 v234, v218, v219
	v_cvt_pk_bf16_f32 v235, v220, v221
	v_cvt_pk_bf16_f32 v236, v222, v223
	v_cvt_pk_bf16_f32 v237, v224, v225
	s_waitcnt lgkmcnt(1)
	v_mfma_f32_32x32x16_bf16 v[66:81], v[206:209], v[122:125], v[66:81]
	v_cvt_pk_bf16_f32 v249, v248, v249
	v_cvt_pk_bf16_f32 v248, v246, v247
	v_cvt_pk_bf16_f32 v247, v244, v245
	v_cvt_pk_bf16_f32 v246, v242, v243
	v_cvt_pk_bf16_f32 v242, v226, v227
	v_cvt_pk_bf16_f32 v243, v228, v229
	v_cvt_pk_bf16_f32 v244, v230, v231
	v_cvt_pk_bf16_f32 v245, v232, v233
	v_mfma_f32_32x32x16_bf16 v[82:97], v[202:205], v[126:129], v[82:97]
	s_waitcnt lgkmcnt(0)
	v_mfma_f32_32x32x16_bf16 v[66:81], v[214:217], v[126:129], v[66:81]
	s_add_i32 s76, s77, 63
	s_cmp_le_i32 s76, s5
	s_cbranch_scc1 .Lff1b_z2
	v_cmp_le_i32_e32 vcc, v165, v195
	s_nop 8
	v_cndmask_b32_e32 v66, v155, v66, vcc
	v_cmp_lt_i32_e32 vcc, v163, v195
	s_nop 1
	v_cndmask_b32_e32 v83, v155, v83, vcc
	v_cmp_le_i32_e32 vcc, v163, v195
	s_nop 1
	v_cndmask_b32_e32 v82, v155, v82, vcc
	v_cmp_le_i32_e32 vcc, v166, v195
	s_nop 1
	v_cndmask_b32_e32 v67, v155, v67, vcc
	v_cmp_le_i32_e32 vcc, v167, v195
	s_nop 1
	v_cndmask_b32_e32 v84, v155, v84, vcc
	v_cmp_le_i32_e32 vcc, v168, v195
	s_nop 1
	v_cndmask_b32_e32 v68, v155, v68, vcc
	v_cmp_le_i32_e32 vcc, v169, v195
	s_nop 1
	v_cndmask_b32_e32 v85, v155, v85, vcc
	v_cmp_le_i32_e32 vcc, v170, v195
	s_nop 1
	v_cndmask_b32_e32 v69, v155, v69, vcc
	v_cmp_le_i32_e32 vcc, v171, v195
	s_nop 1
	v_cndmask_b32_e32 v86, v155, v86, vcc
	v_cmp_le_i32_e32 vcc, v172, v195
	s_nop 1
	v_cndmask_b32_e32 v70, v155, v70, vcc
	v_cmp_le_i32_e32 vcc, v173, v195
	s_nop 1
	v_cndmask_b32_e32 v87, v155, v87, vcc
	v_cmp_le_i32_e32 vcc, v174, v195
	s_nop 1
	v_cndmask_b32_e32 v71, v155, v71, vcc
	v_cmp_le_i32_e32 vcc, v175, v195
	s_nop 1
	v_cndmask_b32_e32 v88, v155, v88, vcc
	v_cmp_le_i32_e32 vcc, v176, v195
	s_nop 1
	v_cndmask_b32_e32 v72, v155, v72, vcc
	v_cmp_le_i32_e32 vcc, v177, v195
	s_nop 1
	v_cndmask_b32_e32 v89, v155, v89, vcc
	v_cmp_le_i32_e32 vcc, v178, v195
	s_nop 1
	v_cndmask_b32_e32 v73, v155, v73, vcc
	v_cmp_le_i32_e32 vcc, v179, v195
	s_nop 1
	v_cndmask_b32_e32 v90, v155, v90, vcc
	v_cmp_le_i32_e32 vcc, v180, v195
	s_nop 1
	v_cndmask_b32_e32 v74, v155, v74, vcc
	v_cmp_le_i32_e32 vcc, v181, v195
	s_nop 1
	v_cndmask_b32_e32 v91, v155, v91, vcc
	v_cmp_le_i32_e32 vcc, v182, v195
	s_nop 1
	v_cndmask_b32_e32 v75, v155, v75, vcc
	v_cmp_le_i32_e32 vcc, v183, v195
	s_nop 1
	v_cndmask_b32_e32 v92, v155, v92, vcc
	v_cmp_le_i32_e32 vcc, v184, v195
	s_nop 1
	v_cndmask_b32_e32 v76, v155, v76, vcc
	v_cmp_le_i32_e32 vcc, v185, v195
	s_nop 1
	v_cndmask_b32_e32 v93, v155, v93, vcc
	v_cmp_le_i32_e32 vcc, v186, v195
	s_nop 1
	v_cndmask_b32_e32 v77, v155, v77, vcc
	v_cmp_le_i32_e32 vcc, v187, v195
	s_nop 1
	v_cndmask_b32_e32 v94, v155, v94, vcc
	v_cmp_le_i32_e32 vcc, v188, v195
	s_nop 1
	v_cndmask_b32_e32 v78, v155, v78, vcc
	v_cmp_le_i32_e32 vcc, v189, v195
	s_nop 1
	v_cndmask_b32_e32 v95, v155, v95, vcc
	v_cmp_le_i32_e32 vcc, v190, v195
	s_nop 1
	v_cndmask_b32_e32 v79, v155, v79, vcc
	v_cmp_le_i32_e32 vcc, v191, v195
	s_nop 1
	v_cndmask_b32_e32 v96, v155, v96, vcc
	v_cmp_le_i32_e32 vcc, v192, v195
	s_nop 1
	v_cndmask_b32_e32 v80, v155, v80, vcc
	v_cmp_le_i32_e32 vcc, v193, v195
	s_nop 1
	v_cndmask_b32_e32 v97, v155, v97, vcc
	v_cmp_le_i32_e32 vcc, v194, v195
	s_nop 1
	v_cndmask_b32_e32 v81, v155, v81, vcc
